# GQA attention loop: all 8 K-fragment ds_reads of each QK^T block issued up front into own registers (v236..251), counted lgkmcnt per MFMA (base: v31)
# baseline (speedup 1.0000x reference)
.LBB0_692:
	ds_read_b128 v[34:37], v138 offset:32768
	ds_read_b128 v[38:41], v138 offset:40960
	ds_read_b128 v[152:155], v142 offset:32768
	ds_read_b128 v[156:159], v142 offset:40960
	ds_read_b128 v[236:239], v144 offset:32768
	ds_read_b128 v[240:243], v144 offset:40960
	ds_read_b128 v[244:247], v143 offset:32768
	ds_read_b128 v[248:251], v143 offset:40960
	v_exp_f32_e32 v151, v106
	v_add_f32_e32 v106, 0, v120
	s_waitcnt lgkmcnt(7)
	v_mfma_f32_32x32x16_bf16 v[50:65], v[34:37], v[78:81], 0
	v_add_f32_e32 v106, v128, v106
	v_add_f32_e32 v106, v121, v106
	v_add_f32_e32 v106, v129, v106
	v_add_f32_e32 v106, v126, v106
	v_add_f32_e32 v106, v149, v106
	v_add_f32_e32 v106, v127, v106
	v_add_f32_e32 v106, v150, v106
	s_waitcnt lgkmcnt(6)
	v_mfma_f32_32x32x16_bf16 v[34:49], v[38:41], v[78:81], 0
	v_add_f32_e32 v106, v112, v106
	v_add_f32_e32 v106, v115, v106
	v_add_f32_e32 v106, v113, v106
	v_add_f32_e32 v106, v116, v106
	v_exp_f32_e32 v111, v108
	v_add_f32_e32 v106, v114, v106
	v_exp_f32_e32 v148, v109
	s_waitcnt lgkmcnt(5)
	v_mfma_f32_32x32x16_bf16 v[50:65], v[152:155], v[70:73], v[50:65]
	v_add_f32_e32 v106, v117, v106
	v_add_f32_e32 v106, v118, v106
	v_add_f32_e32 v106, v119, v106
	v_exp_f32_e32 v102, v102
	v_add_f32_e32 v106, v111, v106
	v_exp_f32_e32 v103, v103
	v_add_f32_e32 v106, v148, v106
	s_waitcnt lgkmcnt(4)
	v_mfma_f32_32x32x16_bf16 v[34:49], v[156:159], v[70:73], v[34:49]
	v_exp_f32_e32 v98, v98
	v_add_f32_e32 v106, v151, v106
	v_exp_f32_e32 v99, v99
	v_exp_f32_e32 v96, v96
	v_exp_f32_e32 v97, v97
	v_exp_f32_e32 v104, v104
	s_waitcnt lgkmcnt(3)
	v_mfma_f32_32x32x16_bf16 v[50:65], v[236:239], v[66:69], v[50:65]
	v_exp_f32_e32 v105, v105
	v_exp_f32_e32 v100, v100
	v_exp_f32_e32 v101, v101
	v_exp_f32_e32 v94, v94
	v_exp_f32_e32 v95, v95
	s_waitcnt lgkmcnt(2)
	v_mfma_f32_32x32x16_bf16 v[34:49], v[240:243], v[66:69], v[34:49]
	s_waitcnt lgkmcnt(1)
	v_mfma_f32_32x32x16_bf16 v[50:65], v[244:247], v[74:77], v[50:65]
	v_exp_f32_e32 v152, v107
	s_nop 0
	v_add_f32_e32 v106, v152, v106
	v_add_f32_e32 v106, v102, v106
	v_add_f32_e32 v106, v103, v106
	v_add_f32_e32 v106, v98, v106
	v_add_f32_e32 v106, v99, v106
	v_add_f32_e32 v106, v96, v106
	v_add_f32_e32 v106, v97, v106
	s_waitcnt lgkmcnt(0)
	v_mfma_f32_32x32x16_bf16 v[34:49], v[248:251], v[74:77], v[34:49]
	v_add_f32_e32 v106, v104, v106
	v_add_f32_e32 v106, v105, v106
	v_add_f32_e32 v106, v100, v106
	v_add_f32_e32 v106, v101, v106
	v_add_f32_e32 v106, v94, v106
	v_add_f32_e32 v146, v95, v106
	v_mov_b32_e32 v147, v146
	v_cvt_pk_bf16_f32 v106, v120, v128
	v_cvt_pk_bf16_f32 v107, v121, v129
	v_cvt_pk_bf16_f32 v108, v126, v149
	v_cvt_pk_bf16_f32 v109, v127, v150
	v_cvt_pk_bf16_f32 v112, v112, v115
	v_cvt_pk_bf16_f32 v113, v113, v116
	v_cvt_pk_bf16_f32 v114, v114, v117
	v_cvt_pk_bf16_f32 v115, v118, v119
	v_cvt_pk_bf16_f32 v116, v111, v148
	v_cvt_pk_bf16_f32 v117, v151, v152
	v_cvt_pk_bf16_f32 v118, v102, v103
	v_cvt_pk_bf16_f32 v119, v98, v99
	v_cvt_pk_bf16_f32 v148, v96, v97
	v_cvt_pk_bf16_f32 v149, v104, v105
	v_cvt_pk_bf16_f32 v150, v100, v101
	s_nop 1
	v_permlane32_swap_b32_e32 v146, v147
	v_permlane32_swap_b32_e32 v106, v108
	v_cvt_pk_bf16_f32 v151, v94, v95
	v_permlane32_swap_b32_e32 v148, v150
	v_permlane32_swap_b32_e32 v107, v109
	v_permlane32_swap_b32_e32 v112, v114
	v_permlane32_swap_b32_e32 v113, v115
	v_permlane32_swap_b32_e32 v116, v118
	v_permlane32_swap_b32_e32 v117, v119
	v_permlane32_swap_b32_e32 v149, v151
	v_readlane_b32 s36, v252, 0
	v_readlane_b32 s37, v252, 1
	s_mov_b64 s[8:9], s[36:37]
	v_lshl_add_u64 v[128:129], v[124:125], 0, s[8:9]
	v_add_co_u32_e32 v94, vcc, s53, v128
	v_lshl_add_u64 v[126:127], v[122:123], 0, s[8:9]
	s_nop 0
	v_addc_co_u32_e32 v95, vcc, 0, v129, vcc
	v_add_co_u32_e32 v98, vcc, s53, v126
	s_mov_b32 s8, 0x1ed67000
	s_nop 0
	v_addc_co_u32_e32 v99, vcc, 0, v127, vcc
	v_add_co_u32_e32 v102, vcc, s8, v126
	global_load_dwordx4 v[94:97], v[94:95], off offset:1088
	s_nop 0
	v_addc_co_u32_e32 v103, vcc, 0, v127, vcc
	global_load_dwordx4 v[98:101], v[98:99], off offset:832
	s_nop 0
	global_load_dwordx4 v[102:105], v[102:103], off offset:2880
	v_readlane_b32 s38, v252, 2
	v_readlane_b32 s39, v252, 3
	v_readlane_b32 s40, v252, 4
	v_readlane_b32 s41, v252, 5
	v_readlane_b32 s42, v252, 6
	v_readlane_b32 s43, v252, 7
	v_readlane_b32 s44, v252, 8
	v_readlane_b32 s45, v252, 9
	v_readlane_b32 s46, v252, 10
	v_readlane_b32 s47, v252, 11
	v_readlane_b32 s48, v252, 12
	v_readlane_b32 s49, v252, 13
	v_readlane_b32 s50, v252, 14
	v_readlane_b32 s51, v252, 15
	ds_read_b64_tr_b16 v[152:153], v137 offset:0
	ds_read_b64_tr_b16 v[154:155], v137 offset:0x400
	ds_read_b64_tr_b16 v[156:157], v137 offset:0x800
	ds_read_b64_tr_b16 v[158:159], v137 offset:0xc00
	ds_read_b64_tr_b16 v[160:161], v137 offset:0x1000
	ds_read_b64_tr_b16 v[162:163], v137 offset:0x1400
	ds_read_b64_tr_b16 v[164:165], v137 offset:0x1800
	ds_read_b64_tr_b16 v[166:167], v137 offset:0x1c00
	s_waitcnt lgkmcnt(0)
	s_nop 0
	v_mfma_f32_32x32x16_bf16 v[2:17], v[106:109], v[152:155], v[2:17]
	ds_read_b64_tr_b16 v[152:153], v137 offset:0x200
	ds_read_b64_tr_b16 v[154:155], v137 offset:0x600
	v_mfma_f32_32x32x16_bf16 v[2:17], v[112:115], v[156:159], v[2:17]
	ds_read_b64_tr_b16 v[156:157], v137 offset:0xa00
	ds_read_b64_tr_b16 v[158:159], v137 offset:0xe00
	v_mfma_f32_32x32x16_bf16 v[2:17], v[116:119], v[160:163], v[2:17]
	ds_read_b64_tr_b16 v[160:161], v137 offset:0x1200
	ds_read_b64_tr_b16 v[162:163], v137 offset:0x1600
	v_mfma_f32_32x32x16_bf16 v[2:17], v[148:151], v[164:167], v[2:17]
	ds_read_b64_tr_b16 v[164:165], v137 offset:0x1a00
	ds_read_b64_tr_b16 v[166:167], v137 offset:0x1e00
	s_waitcnt lgkmcnt(0)
	v_mfma_f32_32x32x16_bf16 v[18:33], v[106:109], v[152:155], v[18:33]
	v_max_f32_e32 v106, v51, v51
	v_max_f32_e32 v107, v50, v50
	v_max_f32_e32 v106, v107, v106
	v_max3_f32 v106, v106, v52, v53
	v_max3_f32 v106, v106, v54, v55
	v_max3_f32 v106, v106, v56, v57
	v_max3_f32 v106, v106, v58, v59
	v_max3_f32 v106, v106, v60, v61
	v_max3_f32 v106, v106, v62, v63
	v_mfma_f32_32x32x16_bf16 v[18:33], v[112:115], v[156:159], v[18:33]
	v_max3_f32 v106, v106, v64, v65
	v_max3_f32 v106, v106, v34, v35
	v_max3_f32 v106, v106, v36, v37
	v_max3_f32 v106, v106, v38, v39
	v_max3_f32 v106, v106, v40, v41
	v_max3_f32 v106, v106, v42, v43
	v_max3_f32 v106, v106, v44, v45
	v_max3_f32 v106, v106, v46, v47
	v_mfma_f32_32x32x16_bf16 v[18:33], v[116:119], v[160:163], v[18:33]
	v_max3_f32 v106, v106, v48, v49
	v_mov_b32_e32 v107, v106
	s_nop 1
	v_permlane32_swap_b32_e32 v106, v107
	v_max_f32_e32 v107, v107, v107
	v_max_f32_e32 v106, v106, v106
	v_max_f32_e32 v106, v106, v107
	v_sub_f32_e32 v107, v106, v110
	v_cmp_ge_f32_e32 vcc, s97, v107
	v_max_f32_e32 v107, v110, v110
	v_max_f32_e32 v106, v107, v106
	v_mfma_f32_32x32x16_bf16 v[18:33], v[148:151], v[164:167], v[18:33]
	v_sub_f32_e32 v107, v110, v106
	v_mul_f32_e32 v107, 0x3e38aa3b, v107
	v_exp_f32_e32 v107, v107
	s_cmp_eq_u64 vcc, exec
	s_cselect_b64 s[8:9], -1, 0
	s_barrier
	s_waitcnt vmcnt(3)
	v_cndmask_b32_e64 v148, v107, 1.0, s[8:9]
	v_cmp_gt_f32_e32 vcc, 1.0, v148
	s_waitcnt vmcnt(3)
	ds_write_b128 v141, v[82:85]
	ds_write_b128 v139, v[90:93] offset:16384
	ds_write_b128 v140, v[86:89] offset:16384
	s_cbranch_vccz .LBB0_696
	s_and_saveexec_b64 s[10:11], s[0:1]
	ds_write_b32 v134, v148 offset:49280
	s_or_b64 exec, exec, s[10:11]
	s_waitcnt lgkmcnt(0)
	v_add_u32_e32 v107, v133, v0
	ds_read_b128 v[112:115], v107 offset:49376
	ds_read_b128 v[116:119], v107 offset:49344
	ds_read_b128 v[150:153], v107 offset:49312
	ds_read_b128 v[154:157], v107 offset:49280
	s_waitcnt lgkmcnt(3)
	v_pk_mul_f32 v[14:15], v[14:15], v[112:113]
	s_waitcnt lgkmcnt(2)
	v_pk_mul_f32 v[10:11], v[10:11], v[116:117]
	s_waitcnt lgkmcnt(1)
	v_pk_mul_f32 v[6:7], v[6:7], v[150:151]
	v_pk_mul_f32 v[16:17], v[16:17], v[114:115]
	v_pk_mul_f32 v[12:13], v[12:13], v[118:119]
	v_pk_mul_f32 v[8:9], v[8:9], v[152:153]
	s_waitcnt lgkmcnt(0)
	v_pk_mul_f32 v[4:5], v[4:5], v[156:157]
	v_pk_mul_f32 v[2:3], v[2:3], v[154:155]
	v_pk_mul_f32 v[30:31], v[30:31], v[112:113]
	v_pk_mul_f32 v[26:27], v[26:27], v[116:117]
	v_pk_mul_f32 v[22:23], v[22:23], v[150:151]
	v_pk_mul_f32 v[32:33], v[32:33], v[114:115]
	v_pk_mul_f32 v[28:29], v[28:29], v[118:119]
	v_pk_mul_f32 v[24:25], v[24:25], v[152:153]
	v_pk_mul_f32 v[20:21], v[20:21], v[156:157]
	v_pk_mul_f32 v[18:19], v[18:19], v[154:155]
.LBB0_696:
	v_cndmask_b32_e64 v149, v106, v110, s[8:9]
	v_mul_f32_e32 v150, 0xbe38aa3b, v149
	v_fmamk_f32 v50, v50, 0x3e38aa3b, v150
	v_fmamk_f32 v51, v51, 0x3e38aa3b, v150
	v_fmamk_f32 v52, v52, 0x3e38aa3b, v150
	v_fmamk_f32 v53, v53, 0x3e38aa3b, v150
	v_fmamk_f32 v54, v54, 0x3e38aa3b, v150
	v_fmamk_f32 v55, v55, 0x3e38aa3b, v150
	v_fmamk_f32 v56, v56, 0x3e38aa3b, v150
	v_fmamk_f32 v57, v57, 0x3e38aa3b, v150
	v_fmamk_f32 v58, v58, 0x3e38aa3b, v150
	v_fmamk_f32 v59, v59, 0x3e38aa3b, v150
	v_fmamk_f32 v60, v60, 0x3e38aa3b, v150
	v_fmamk_f32 v61, v61, 0x3e38aa3b, v150
	v_fmamk_f32 v62, v62, 0x3e38aa3b, v150
	v_fmamk_f32 v63, v63, 0x3e38aa3b, v150
	v_fmamk_f32 v64, v64, 0x3e38aa3b, v150
	v_fmamk_f32 v65, v65, 0x3e38aa3b, v150
	v_exp_f32_e32 v106, v50
	v_exp_f32_e32 v121, v51
	v_exp_f32_e32 v107, v52
	v_exp_f32_e32 v120, v53
	v_exp_f32_e32 v108, v54
	v_exp_f32_e32 v119, v55
	v_exp_f32_e32 v109, v56
	v_exp_f32_e32 v118, v57
	v_exp_f32_e32 v110, v58
	v_exp_f32_e32 v117, v59
	v_exp_f32_e32 v111, v60
	v_exp_f32_e32 v116, v61
	v_exp_f32_e32 v112, v62
	v_exp_f32_e32 v115, v63
	v_exp_f32_e32 v113, v64
	v_exp_f32_e32 v114, v65
	v_fmamk_f32 v152, v39, 0x3e38aa3b, v150
	v_fmamk_f32 v151, v46, 0x3e38aa3b, v150
	v_fmamk_f32 v159, v34, 0x3e38aa3b, v150
	v_fmamk_f32 v160, v35, 0x3e38aa3b, v150
	v_fmamk_f32 v161, v36, 0x3e38aa3b, v150
	v_fmamk_f32 v162, v37, 0x3e38aa3b, v150
	v_fmamk_f32 v163, v38, 0x3e38aa3b, v150
	v_fmamk_f32 v153, v40, 0x3e38aa3b, v150
	v_fmamk_f32 v154, v41, 0x3e38aa3b, v150
	v_fmamk_f32 v155, v42, 0x3e38aa3b, v150
	v_fmamk_f32 v156, v43, 0x3e38aa3b, v150
	v_fmamk_f32 v157, v44, 0x3e38aa3b, v150
	v_fmamk_f32 v158, v45, 0x3e38aa3b, v150
	v_fmamk_f32 v164, v47, 0x3e38aa3b, v150
	v_fmamk_f32 v165, v48, 0x3e38aa3b, v150
	v_fmac_f32_e32 v150, 0x3e38aa3b, v49
	s_waitcnt lgkmcnt(0)
	s_barrier
	ds_read_b128 v[34:37], v138 offset:16384
	ds_read_b128 v[38:41], v138 offset:24576
	ds_read_b128 v[166:169], v142 offset:16384
	ds_read_b128 v[170:173], v142 offset:24576
	ds_read_b128 v[236:239], v144 offset:16384
	ds_read_b128 v[240:243], v144 offset:24576
	ds_read_b128 v[244:247], v143 offset:16384
	ds_read_b128 v[248:251], v143 offset:24576
	v_exp_f32_e32 v159, v159
	v_exp_f32_e32 v160, v160
	s_waitcnt lgkmcnt(7)
	v_mfma_f32_32x32x16_bf16 v[50:65], v[34:37], v[78:81], 0
	v_exp_f32_e32 v161, v161
	v_exp_f32_e32 v162, v162
	v_exp_f32_e32 v163, v163
	v_exp_f32_e32 v153, v153
	v_exp_f32_e32 v154, v154
	v_exp_f32_e32 v155, v155
	v_exp_f32_e32 v156, v156
	s_waitcnt lgkmcnt(6)
	v_mfma_f32_32x32x16_bf16 v[34:49], v[38:41], v[78:81], 0
	v_exp_f32_e32 v157, v157
	v_exp_f32_e32 v158, v158
	v_exp_f32_e32 v164, v164
	v_exp_f32_e32 v165, v165
	v_exp_f32_e32 v150, v150
	s_waitcnt lgkmcnt(5)
	v_mfma_f32_32x32x16_bf16 v[50:65], v[166:169], v[70:73], v[50:65]
	s_waitcnt lgkmcnt(4)
	v_mfma_f32_32x32x16_bf16 v[34:49], v[170:173], v[70:73], v[34:49]
	s_waitcnt lgkmcnt(3)
	v_mfma_f32_32x32x16_bf16 v[50:65], v[236:239], v[66:69], v[50:65]
	s_waitcnt lgkmcnt(2)
	v_mfma_f32_32x32x16_bf16 v[34:49], v[240:243], v[66:69], v[34:49]
	s_waitcnt lgkmcnt(1)
	v_mfma_f32_32x32x16_bf16 v[50:65], v[244:247], v[74:77], v[50:65]
	v_exp_f32_e32 v167, v151
	v_add_f32_e32 v151, 0, v106
	v_add_f32_e32 v151, v121, v151
	v_add_f32_e32 v151, v107, v151
	v_add_f32_e32 v151, v120, v151
	v_add_f32_e32 v151, v108, v151
	v_add_f32_e32 v151, v119, v151
	v_add_f32_e32 v151, v109, v151
	v_add_f32_e32 v151, v118, v151
	v_add_f32_e32 v151, v110, v151
	v_add_f32_e32 v151, v117, v151
	v_add_f32_e32 v151, v111, v151
	v_add_f32_e32 v151, v116, v151
	v_add_f32_e32 v151, v112, v151
	v_add_f32_e32 v151, v115, v151
	v_add_f32_e32 v151, v113, v151
	v_add_f32_e32 v151, v114, v151
	v_add_f32_e32 v151, v159, v151
	v_exp_f32_e32 v166, v152
	v_add_f32_e32 v151, v160, v151
	v_add_f32_e32 v151, v161, v151
	v_add_f32_e32 v151, v162, v151
	v_add_f32_e32 v151, v163, v151
	v_add_f32_e32 v151, v166, v151
	v_add_f32_e32 v151, v153, v151
	v_add_f32_e32 v151, v154, v151
	v_add_f32_e32 v151, v155, v151
	v_add_f32_e32 v151, v156, v151
	s_waitcnt lgkmcnt(0)
	v_mfma_f32_32x32x16_bf16 v[34:49], v[248:251], v[74:77], v[34:49]
	v_add_f32_e32 v151, v157, v151
	v_add_f32_e32 v151, v158, v151
	v_add_f32_e32 v151, v167, v151
	v_add_f32_e32 v151, v164, v151
	v_add_f32_e32 v151, v165, v151
	v_add_f32_e32 v151, v150, v151
	v_mov_b32_e32 v152, v151
	v_cvt_pk_bf16_f32 v106, v106, v121
	v_cvt_pk_bf16_f32 v107, v107, v120
	v_cvt_pk_bf16_f32 v108, v108, v119
	v_cvt_pk_bf16_f32 v109, v109, v118
	v_cvt_pk_bf16_f32 v110, v110, v117
	v_cvt_pk_bf16_f32 v111, v111, v116
	v_cvt_pk_bf16_f32 v112, v112, v115
	v_cvt_pk_bf16_f32 v113, v113, v114
	v_cvt_pk_bf16_f32 v114, v159, v160
	v_cvt_pk_bf16_f32 v115, v161, v162
	v_cvt_pk_bf16_f32 v116, v163, v166
	v_cvt_pk_bf16_f32 v117, v153, v154
	v_cvt_pk_bf16_f32 v118, v155, v156
	v_cvt_pk_bf16_f32 v119, v157, v158
	v_cvt_pk_bf16_f32 v120, v167, v164
	v_cvt_pk_bf16_f32 v121, v165, v150
	s_nop 1
	v_permlane32_swap_b32_e32 v151, v152
	v_permlane32_swap_b32_e32 v106, v108
	v_permlane32_swap_b32_e32 v107, v109
	v_permlane32_swap_b32_e32 v110, v112
	v_permlane32_swap_b32_e32 v111, v113
	v_permlane32_swap_b32_e32 v114, v116
	v_permlane32_swap_b32_e32 v115, v117
	v_permlane32_swap_b32_e32 v118, v120
	v_permlane32_swap_b32_e32 v119, v121
	s_cmp_ge_u32 s19, s18
	s_cselect_b64 s[10:11], -1, 0
	s_and_b64 vcc, exec, s[10:11]
	s_cbranch_vccnz .LBB0_698
	v_add_co_u32_e32 v82, vcc, 0x1ed86000, v128
	s_nop 1
	v_addc_co_u32_e32 v83, vcc, 0, v129, vcc
	v_add_co_u32_e32 v86, vcc, 0x1ed86000, v126
	global_load_dwordx4 v[82:85], v[82:83], off offset:1088
	s_nop 0
	v_addc_co_u32_e32 v87, vcc, 0, v127, vcc
	v_add_co_u32_e32 v88, vcc, 0x1eda4000, v126
	s_nop 1
	v_addc_co_u32_e32 v89, vcc, 0, v127, vcc
	global_load_dwordx4 v[90:93], v[86:87], off offset:832
	s_nop 0
	global_load_dwordx4 v[86:89], v[88:89], off offset:2880
